# up-proj: in the last round neighbouring workgroups swap units so no workgroup gets two sample-row tiles (their epilogue is slower); plus the conv-state warm-up loads
# baseline (speedup 1.0000x reference)
.LBB0_1370:
	s_add_i32 s65, s66, 1
	s_mul_i32 s6, s65, s37
	s_mul_hi_i32 s7, s65, s37
	s_add_u32 s6, s6, s36
	s_addc_u32 s7, s7, s64
	s_cmp_eq_u32 s65, 22
	s_cbranch_scc0 .Lmy_up_noswap
	s_xor_b32 s6, s6, 1
.Lmy_up_noswap:
	v_mov_b64_e32 v[128:129], 0x162c
	v_cmp_lt_i64_e64 s[40:41], s[6:7], v[128:129]
	v_mov_b64_e32 v[128:129], 0x162b
	v_cmp_gt_i64_e64 s[38:39], s[6:7], v[128:129]
	s_and_b64 vcc, exec, s[38:39]
	s_cbranch_vccnz .LBB0_1376
	s_ashr_i32 s7, s6, 31
	s_lshr_b32 s7, s7, 29
	s_add_i32 s8, s6, s7
	s_and_b32 s7, s8, -8
	s_sub_i32 s9, s6, s7
	s_cmp_gt_i32 s9, 3
	s_mov_b64 s[6:7], -1
	s_cbranch_scc0 .LBB0_1373
	s_mul_i32 s6, s9, 0x2c5
	s_add_i32 s18, s6, 4
	s_mov_b64 s[6:7], 0
